# combo20: combo11 + diff-attention off-diagonal tiles issue all 8 K-fragment and 16 V-fragment LDS reads at the top of the tile (K4..K7 into the later exp registers, V into free VGPRs); no LDS waits be
# speedup vs baseline: 1.0118x; 1.0001x over previous
; template <int TYPE> __device__ __forceinline__ void attn_unit(const AttnCtx& C, int b, int h, int qb, LAS unsigned char* lds, int tid_in, unsigned* counter) {
;     ...
;             const bool active = (TYPE == 2) ? (t >= cq - 8 && t <= cq) : (TYPE == 0) ? (t <= cq && (float)(256 * qb + 32 * w - 64 * t - 63) < dmax) : (t <= cq && t >= tfirst);
;             if (active) {
;                 f32x16 p0, p1;
;                 const LAS unsigned char* kp = Kb + bo + hi * 1024 + r32 * 16;
; #pragma unroll
;                 for (int d0 = 0; d0 < 4; ++d0) {
;                     const bf16x8 a0 = *(const LAS bf16x8*)(kp + d0 * 2048), a1 = *(const LAS bf16x8*)(kp + d0 * 2048 + 512);
;                     if (d0 == 0) { p0 = MFMA32(a0, qr[0], (TYPE == 1 ? cvec : zvec)); p1 = MFMA32(a1, qr[0], (TYPE == 1 ? cvec : zvec)); }
;                     else { p0 = MFMA32(a0, qr[d0], p0); p1 = MFMA32(a1, qr[d0], p1); }
;                 }
;                 const int xi = sq - 64 * t - 4 * hi;
;                 if (TYPE == 0) {
;                     const float xf = (float)xi;
; #pragma unroll
;                     for (int r = 0; r < 16; ++r) { const float c = (float)((r & 3) + 8 * (r >> 2));
;                         p0[r] = fast_exp2(p0[r] - sl2 * fabsf(xf - c)); p1[r] = fast_exp2(p1[r] - sl2 * fabsf(xf - (c + 32.f))); }
;                 } else if (TYPE == 1) {
;                     const LAS float* fp = Fb + (t & 3) * 64 + 4 * hi;
; #pragma unroll
;                     for (int g = 0; g < 4; ++g) { const f32x4 fa = *(const LAS f32x4*)(fp + 8 * g), fb2 = *(const LAS f32x4*)(fp + 32 + 8 * g);
; #pragma unroll
;                         for (int i = 0; i < 4; i += 2) {
;                             const f32x2_t d0_ = (f32x2_t){p0[4 * g + i], p0[4 * g + i + 1]} - (f32x2_t){fa[i], fa[i + 1]}, d1_ = (f32x2_t){p1[4 * g + i], p1[4 * g + i + 1]} - (f32x2_t){fb2[i], fb2[i + 1]};
;                             p0[4 * g + i] = fast_exp2(d0_[0]); p0[4 * g + i + 1] = fast_exp2(d0_[1]); p1[4 * g + i] = fast_exp2(d1_[0]); p1[4 * g + i + 1] = fast_exp2(d1_[1]); } }
;                     if (t == cq) { const int qrel = 32 * (w & 1) + r32;
; #pragma unroll
;                         for (int r = 0; r < 16; ++r) { const int kv = crow(r, hi); if (kv > qrel) p0[r] = 0.f; if (kv + 32 > qrel) p1[r] = 0.f; } }
;                 } else {
;                     if (cq - t >= 3) { const float bc = relb[256];
.LBB0_438:
	s_cmp_gt_i32 s4, s14
	s_cbranch_scc1 .LBB0_433
	s_sub_i32 s6, s1, 63
	v_cvt_f32_i32_e32 v32, s6
	v_cmp_ngt_f32_e32 vcc, v168, v32
	s_cbranch_vccnz .LBB0_433
	s_cmp_eq_u32 s4, s14
	s_cbranch_scc1 .Lt0diag_4
	v_add_u32_e32 v118, s5, v171
	v_add_u32_e32 v213, s1, v172
	v_cvt_f32_i32_e32 v213, v213
	v_mul_f32_e64 v210, -v167, v213
	ds_read_b128 v[202:205], v118
	ds_read_b128 v[206:209], v118 offset:512
	ds_read_b128 v[110:113], v118 offset:2048
	ds_read_b128 v[114:117], v118 offset:2560
	ds_read_b128 v[122:125], v118 offset:4608
	ds_read_b128 v[126:129], v118 offset:6144
	ds_read_b128 v[130:133], v118 offset:6656
	ds_read_b128 v[118:121], v118 offset:4096
	v_add_u32_e32 v134, s5, v170
	ds_read_b64_tr_b16 v[214:215], v134 offset:32768
	ds_read_b64_tr_b16 v[216:217], v134 offset:33280
	ds_read_b64_tr_b16 v[218:219], v134 offset:33792
	ds_read_b64_tr_b16 v[220:221], v134 offset:34304
	ds_read_b64_tr_b16 v[222:223], v134 offset:34816
	ds_read_b64_tr_b16 v[224:225], v134 offset:35328
	ds_read_b64_tr_b16 v[226:227], v134 offset:35840
	ds_read_b64_tr_b16 v[228:229], v134 offset:36352
	ds_read_b64_tr_b16 v[230:231], v134 offset:36864
	ds_read_b64_tr_b16 v[232:233], v134 offset:37376
	ds_read_b64_tr_b16 v[234:235], v134 offset:37888
	ds_read_b64_tr_b16 v[236:237], v134 offset:38400
	ds_read_b64_tr_b16 v[238:239], v134 offset:38912
	ds_read_b64_tr_b16 v[240:241], v134 offset:39424
	ds_read_b64_tr_b16 v[242:243], v134 offset:39936
	ds_read_b64_tr_b16 v[244:245], v134 offset:40448
	v_mov_b32_e32 v48, v210
	v_fmamk_f32 v49, v167, 0x3f800000, v210
	v_fmamk_f32 v50, v167, 0x40000000, v210
	v_fmamk_f32 v51, v167, 0x40400000, v210
	v_fmamk_f32 v52, v167, 0x41000000, v210
	v_fmamk_f32 v53, v167, 0x41100000, v210
	v_fmamk_f32 v54, v167, 0x41200000, v210
	v_fmamk_f32 v55, v167, 0x41300000, v210
	v_fmamk_f32 v56, v167, 0x41800000, v210
	v_fmamk_f32 v57, v167, 0x41880000, v210
	v_fmamk_f32 v58, v167, 0x41900000, v210
	v_fmamk_f32 v59, v167, 0x41980000, v210
	v_fmamk_f32 v60, v167, 0x41c00000, v210
	v_fmamk_f32 v61, v167, 0x41c80000, v210
	v_fmamk_f32 v62, v167, 0x41d00000, v210
	v_fmamk_f32 v63, v167, 0x41d80000, v210
	v_fmamk_f32 v32, v167, 0x42000000, v210
	v_fmamk_f32 v33, v167, 0x42040000, v210
	v_fmamk_f32 v34, v167, 0x42080000, v210
	v_fmamk_f32 v35, v167, 0x420c0000, v210
	v_fmamk_f32 v36, v167, 0x42200000, v210
	v_fmamk_f32 v37, v167, 0x42240000, v210
	v_fmamk_f32 v38, v167, 0x42280000, v210
	v_fmamk_f32 v39, v167, 0x422c0000, v210
	v_fmamk_f32 v40, v167, 0x42400000, v210
	v_fmamk_f32 v41, v167, 0x42440000, v210
	v_fmamk_f32 v42, v167, 0x42480000, v210
	v_fmamk_f32 v43, v167, 0x424c0000, v210
	v_fmamk_f32 v44, v167, 0x42600000, v210
	v_fmamk_f32 v45, v167, 0x42640000, v210
	v_fmamk_f32 v46, v167, 0x42680000, v210
	v_fmamk_f32 v47, v167, 0x426c0000, v210
	s_waitcnt vmcnt(7)
	s_waitcnt lgkmcnt(15)
	v_mfma_f32_32x32x16_bf16 v[48:63], v[202:205], v[64:67], v[48:63]
	v_mfma_f32_32x32x16_bf16 v[32:47], v[206:209], v[64:67], v[32:47]
	s_waitcnt vmcnt(6)
	v_mfma_f32_32x32x16_bf16 v[32:47], v[114:117], v[68:71], v[32:47]
	v_mfma_f32_32x32x16_bf16 v[48:63], v[110:113], v[68:71], v[48:63]
	s_waitcnt vmcnt(5)
	v_mfma_f32_32x32x16_bf16 v[32:47], v[122:125], v[72:75], v[32:47]
	v_mfma_f32_32x32x16_bf16 v[48:63], v[118:121], v[72:75], v[48:63]
	s_waitcnt vmcnt(4)
	v_mfma_f32_32x32x16_bf16 v[32:47], v[130:133], v[76:79], v[32:47]
	v_mfma_f32_32x32x16_bf16 v[48:63], v[126:129], v[76:79], v[48:63]
	s_nop 11
	v_exp_f32_e32 v32, v32
	v_exp_f32_e32 v110, v52
	v_exp_f32_e32 v112, v36
	v_exp_f32_e32 v111, v53
	v_exp_f32_e32 v113, v37
	v_exp_f32_e32 v114, v54
	v_exp_f32_e32 v116, v38
	v_exp_f32_e32 v115, v55
	v_exp_f32_e32 v117, v39
	v_exp_f32_e32 v118, v56
	v_exp_f32_e32 v120, v40
	v_exp_f32_e32 v119, v57
	v_exp_f32_e32 v121, v41
	v_exp_f32_e32 v122, v58
	v_exp_f32_e32 v124, v42
	v_exp_f32_e32 v123, v59
	v_exp_f32_e32 v125, v43
	v_exp_f32_e32 v126, v60
	v_exp_f32_e32 v128, v44
	v_exp_f32_e32 v127, v61
	v_exp_f32_e32 v129, v45
	v_exp_f32_e32 v48, v48
	v_exp_f32_e32 v49, v49
	v_exp_f32_e32 v50, v50
	v_exp_f32_e32 v51, v51
	v_exp_f32_e32 v130, v62
	v_exp_f32_e32 v132, v46
	v_exp_f32_e32 v131, v63
	v_cvt_pk_bf16_f32 v36, v48, v49
	v_cvt_pk_bf16_f32 v37, v50, v51
	v_cvt_pk_bf16_f32 v38, v110, v111
	v_cvt_pk_bf16_f32 v39, v114, v115
	s_waitcnt lgkmcnt(0)
	s_nop 0
	v_mfma_f32_32x32x16_bf16 v[16:31], v[36:39], v[214:217], v[16:31]
	v_cvt_pk_bf16_f32 v52, v118, v119
	v_cvt_pk_bf16_f32 v53, v122, v123
	v_cvt_pk_bf16_f32 v54, v126, v127
	v_cvt_pk_bf16_f32 v55, v130, v131
	v_exp_f32_e32 v33, v33
	v_exp_f32_e32 v34, v34
	v_exp_f32_e32 v35, v35
	s_waitcnt lgkmcnt(0)
	v_mfma_f32_32x32x16_bf16 v[16:31], v[52:55], v[218:221], v[16:31]
	v_exp_f32_e32 v133, v47
	v_cvt_pk_bf16_f32 v40, v32, v33
	v_cvt_pk_bf16_f32 v41, v34, v35
	v_cvt_pk_bf16_f32 v42, v112, v113
	v_cvt_pk_bf16_f32 v43, v116, v117
	s_waitcnt lgkmcnt(0)
	s_nop 0
	v_mfma_f32_32x32x16_bf16 v[16:31], v[40:43], v[222:225], v[16:31]
	v_cvt_pk_bf16_f32 v56, v120, v121
	v_cvt_pk_bf16_f32 v57, v124, v125
	v_cvt_pk_bf16_f32 v58, v128, v129
	v_cvt_pk_bf16_f32 v59, v132, v133
	s_waitcnt lgkmcnt(0)
	s_nop 0
	v_mfma_f32_32x32x16_bf16 v[16:31], v[56:59], v[226:229], v[16:31]
	s_waitcnt lgkmcnt(2)
	v_mfma_f32_32x32x16_bf16 v[0:15], v[36:39], v[230:233], v[0:15]
	v_add_f32_e64 v36, v48, 0
	v_add_f32_e64 v37, v49, 0
	v_add_f32_e64 v32, v32, v36
	v_add_f32_e64 v33, v33, v37
	v_add_f32_e64 v32, v50, v32
	v_add_f32_e64 v33, v51, v33
	v_pk_add_f32 v[32:33], v[34:35], v[32:33]
	s_waitcnt lgkmcnt(0)
	v_mfma_f32_32x32x16_bf16 v[0:15], v[52:55], v[234:237], v[0:15]
	v_add_f32_e64 v32, v110, v32
	v_add_f32_e64 v33, v111, v33
	v_add_f32_e64 v32, v112, v32
	v_add_f32_e64 v33, v113, v33
	v_add_f32_e64 v32, v114, v32
	v_add_f32_e64 v33, v115, v33
	v_pk_add_f32 v[36:37], v[116:117], v[32:33]
	s_waitcnt lgkmcnt(0)
	v_mfma_f32_32x32x16_bf16 v[0:15], v[40:43], v[238:241], v[0:15]
	v_add_f32_e64 v36, v118, v36
	v_add_f32_e64 v37, v119, v37
	v_add_f32_e64 v44, v120, v36
	v_add_f32_e64 v45, v121, v37
	v_pk_add_f32 v[32:33], v[122:123], v[44:45]
	s_nop 0
	v_pk_add_f32 v[32:33], v[124:125], v[32:33]
	s_waitcnt lgkmcnt(0)
	v_mfma_f32_32x32x16_bf16 v[0:15], v[56:59], v[242:245], v[0:15]
	v_add_f32_e64 v32, v126, v32
	v_add_f32_e64 v33, v127, v33
	v_add_f32_e64 v32, v128, v32
	v_add_f32_e64 v33, v129, v33
	v_add_f32_e64 v32, v130, v32
	v_add_f32_e64 v33, v131, v33
	v_pk_add_f32 v[32:33], v[132:133], v[32:33]
	s_nop 0
	v_add_f32_e32 v32, v32, v33
	v_add_f32_e32 v109, v109, v32
	s_branch .LBB0_433

; template <int TYPE> __device__ __forceinline__ void attn_unit(const AttnCtx& C, int b, int h, int qb, LAS unsigned char* lds, int tid_in, unsigned* counter) {
;     ...
;             const bool active = (TYPE == 2) ? (t >= cq - 8 && t <= cq) : (TYPE == 0) ? (t <= cq && (float)(256 * qb + 32 * w - 64 * t - 63) < dmax) : (t <= cq && t >= tfirst);
;             if (active) {
;                 f32x16 p0, p1;
;                 const LAS unsigned char* kp = Kb + bo + hi * 1024 + r32 * 16;
; #pragma unroll
;                 for (int d0 = 0; d0 < 4; ++d0) {
;                     const bf16x8 a0 = *(const LAS bf16x8*)(kp + d0 * 2048), a1 = *(const LAS bf16x8*)(kp + d0 * 2048 + 512);
;                     if (d0 == 0) { p0 = MFMA32(a0, qr[0], (TYPE == 1 ? cvec : zvec)); p1 = MFMA32(a1, qr[0], (TYPE == 1 ? cvec : zvec)); }
;                     else { p0 = MFMA32(a0, qr[d0], p0); p1 = MFMA32(a1, qr[d0], p1); }
;                 }
;                 const int xi = sq - 64 * t - 4 * hi;
;                 if (TYPE == 0) {
;                     const float xf = (float)xi;
; #pragma unroll
;                     for (int r = 0; r < 16; ++r) { const float c = (float)((r & 3) + 8 * (r >> 2));
;                         p0[r] = fast_exp2(p0[r] - sl2 * fabsf(xf - c)); p1[r] = fast_exp2(p1[r] - sl2 * fabsf(xf - (c + 32.f))); }
;                 } else if (TYPE == 1) {
;                     const LAS float* fp = Fb + (t & 3) * 64 + 4 * hi;
; #pragma unroll
;                     for (int g = 0; g < 4; ++g) { const f32x4 fa = *(const LAS f32x4*)(fp + 8 * g), fb2 = *(const LAS f32x4*)(fp + 32 + 8 * g);
; #pragma unroll
;                         for (int i = 0; i < 4; i += 2) {
;                             const f32x2_t d0_ = (f32x2_t){p0[4 * g + i], p0[4 * g + i + 1]} - (f32x2_t){fa[i], fa[i + 1]}, d1_ = (f32x2_t){p1[4 * g + i], p1[4 * g + i + 1]} - (f32x2_t){fb2[i], fb2[i + 1]};
;                             p0[4 * g + i] = fast_exp2(d0_[0]); p0[4 * g + i + 1] = fast_exp2(d0_[1]); p1[4 * g + i] = fast_exp2(d1_[0]); p1[4 * g + i + 1] = fast_exp2(d1_[1]); } }
;                     if (t == cq) { const int qrel = 32 * (w & 1) + r32;
; #pragma unroll
;                         for (int r = 0; r < 16; ++r) { const int kv = crow(r, hi); if (kv > qrel) p0[r] = 0.f; if (kv + 32 > qrel) p1[r] = 0.f; } }
;                 } else {
;                     if (cq - t >= 3) { const float bc = relb[256];
.LBB0_454:
	s_cmp_gt_i32 s15, s14
	s_cbranch_scc1 .LBB0_445
	s_sub_i32 s0, s6, 63
	s_waitcnt vmcnt(15)
	v_cvt_f32_i32_e32 v64, s0
	v_cmp_ngt_f32_e32 vcc, v168, v64
	s_cbranch_vccnz .LBB0_445
	s_cmp_eq_u32 s15, s14
	s_cbranch_scc1 .Lt0diag_3
	v_add_u32_e32 v184, s16, v171
	v_add_u32_e32 v213, s6, v172
	v_cvt_f32_i32_e32 v213, v213
	v_mul_f32_e64 v210, -v167, v213
	ds_read_b128 v[202:205], v184
	ds_read_b128 v[206:209], v184 offset:512
	ds_read_b128 v[176:179], v184 offset:2048
	ds_read_b128 v[180:183], v184 offset:2560
	ds_read_b128 v[188:191], v184 offset:4608
	ds_read_b128 v[192:195], v184 offset:6144
	ds_read_b128 v[196:199], v184 offset:6656
	ds_read_b128 v[184:187], v184 offset:4096
	s_waitcnt vmcnt(14)
	v_add_u32_e32 v200, s16, v170
	ds_read_b64_tr_b16 v[214:215], v200 offset:32768
	ds_read_b64_tr_b16 v[216:217], v200 offset:33280
	ds_read_b64_tr_b16 v[218:219], v200 offset:33792
	ds_read_b64_tr_b16 v[220:221], v200 offset:34304
	ds_read_b64_tr_b16 v[222:223], v200 offset:34816
	ds_read_b64_tr_b16 v[224:225], v200 offset:35328
	ds_read_b64_tr_b16 v[226:227], v200 offset:35840
	ds_read_b64_tr_b16 v[228:229], v200 offset:36352
	ds_read_b64_tr_b16 v[230:231], v200 offset:36864
	ds_read_b64_tr_b16 v[232:233], v200 offset:37376
	ds_read_b64_tr_b16 v[234:235], v200 offset:37888
	ds_read_b64_tr_b16 v[236:237], v200 offset:38400
	ds_read_b64_tr_b16 v[238:239], v200 offset:38912
	ds_read_b64_tr_b16 v[240:241], v200 offset:39424
	ds_read_b64_tr_b16 v[242:243], v200 offset:39936
	ds_read_b64_tr_b16 v[244:245], v200 offset:40448
	v_mov_b32_e32 v80, v210
	v_fmamk_f32 v81, v167, 0x3f800000, v210
	v_fmamk_f32 v82, v167, 0x40000000, v210
	v_fmamk_f32 v83, v167, 0x40400000, v210
	v_fmamk_f32 v84, v167, 0x41000000, v210
	v_fmamk_f32 v85, v167, 0x41100000, v210
	v_fmamk_f32 v86, v167, 0x41200000, v210
	v_fmamk_f32 v87, v167, 0x41300000, v210
	v_fmamk_f32 v88, v167, 0x41800000, v210
	v_fmamk_f32 v89, v167, 0x41880000, v210
	v_fmamk_f32 v90, v167, 0x41900000, v210
	v_fmamk_f32 v91, v167, 0x41980000, v210
	v_fmamk_f32 v92, v167, 0x41c00000, v210
	v_fmamk_f32 v93, v167, 0x41c80000, v210
	v_fmamk_f32 v94, v167, 0x41d00000, v210
	v_fmamk_f32 v95, v167, 0x41d80000, v210
	v_fmamk_f32 v64, v167, 0x42000000, v210
	v_fmamk_f32 v65, v167, 0x42040000, v210
	v_fmamk_f32 v66, v167, 0x42080000, v210
	v_fmamk_f32 v67, v167, 0x420c0000, v210
	v_fmamk_f32 v68, v167, 0x42200000, v210
	v_fmamk_f32 v69, v167, 0x42240000, v210
	v_fmamk_f32 v70, v167, 0x42280000, v210
	v_fmamk_f32 v71, v167, 0x422c0000, v210
	v_fmamk_f32 v72, v167, 0x42400000, v210
	v_fmamk_f32 v73, v167, 0x42440000, v210
	v_fmamk_f32 v74, v167, 0x42480000, v210
	v_fmamk_f32 v75, v167, 0x424c0000, v210
	v_fmamk_f32 v76, v167, 0x42600000, v210
	v_fmamk_f32 v77, v167, 0x42640000, v210
	v_fmamk_f32 v78, v167, 0x42680000, v210
	v_fmamk_f32 v79, v167, 0x426c0000, v210
	s_waitcnt vmcnt(7)
	s_waitcnt lgkmcnt(15)
	v_mfma_f32_32x32x16_bf16 v[80:95], v[202:205], v[112:115], v[80:95]
	v_mfma_f32_32x32x16_bf16 v[64:79], v[206:209], v[112:115], v[64:79]
	s_waitcnt vmcnt(6)
	v_mfma_f32_32x32x16_bf16 v[64:79], v[180:183], v[116:119], v[64:79]
	v_mfma_f32_32x32x16_bf16 v[80:95], v[176:179], v[116:119], v[80:95]
	s_waitcnt vmcnt(5)
	v_mfma_f32_32x32x16_bf16 v[64:79], v[188:191], v[120:123], v[64:79]
	v_mfma_f32_32x32x16_bf16 v[80:95], v[184:187], v[120:123], v[80:95]
	s_waitcnt vmcnt(4)
	v_mfma_f32_32x32x16_bf16 v[64:79], v[196:199], v[124:127], v[64:79]
	v_mfma_f32_32x32x16_bf16 v[80:95], v[192:195], v[124:127], v[80:95]
	s_nop 11
	v_exp_f32_e32 v64, v64
	v_exp_f32_e32 v176, v84
	v_exp_f32_e32 v178, v68
	v_exp_f32_e32 v177, v85
	v_exp_f32_e32 v179, v69
	v_exp_f32_e32 v180, v86
	v_exp_f32_e32 v182, v70
	v_exp_f32_e32 v181, v87
	v_exp_f32_e32 v183, v71
	v_exp_f32_e32 v184, v88
	v_exp_f32_e32 v186, v72
	v_exp_f32_e32 v185, v89
	v_exp_f32_e32 v187, v73
	v_exp_f32_e32 v188, v90
	v_exp_f32_e32 v190, v74
	v_exp_f32_e32 v189, v91
	v_exp_f32_e32 v191, v75
	v_exp_f32_e32 v192, v92
	v_exp_f32_e32 v194, v76
	v_exp_f32_e32 v193, v93
	v_exp_f32_e32 v195, v77
	v_exp_f32_e32 v80, v80
	v_exp_f32_e32 v81, v81
	v_exp_f32_e32 v82, v82
	v_exp_f32_e32 v83, v83
	v_exp_f32_e32 v196, v94
	v_exp_f32_e32 v198, v78
	v_exp_f32_e32 v197, v95
	v_cvt_pk_bf16_f32 v68, v80, v81
	v_cvt_pk_bf16_f32 v69, v82, v83
	v_cvt_pk_bf16_f32 v70, v176, v177
	v_cvt_pk_bf16_f32 v71, v180, v181
	s_waitcnt lgkmcnt(0)
	s_nop 0
	v_mfma_f32_32x32x16_bf16 v[48:63], v[68:71], v[214:217], v[48:63]
	v_cvt_pk_bf16_f32 v84, v184, v185
	v_cvt_pk_bf16_f32 v85, v188, v189
	v_cvt_pk_bf16_f32 v86, v192, v193
	v_cvt_pk_bf16_f32 v87, v196, v197
	v_exp_f32_e32 v65, v65
	v_exp_f32_e32 v66, v66
	v_exp_f32_e32 v67, v67
	s_waitcnt lgkmcnt(0)
	v_mfma_f32_32x32x16_bf16 v[48:63], v[84:87], v[218:221], v[48:63]
	v_exp_f32_e32 v199, v79
	v_cvt_pk_bf16_f32 v72, v64, v65
	v_cvt_pk_bf16_f32 v73, v66, v67
	v_cvt_pk_bf16_f32 v74, v178, v179
	v_cvt_pk_bf16_f32 v75, v182, v183
	s_waitcnt lgkmcnt(0)
	s_nop 0
	v_mfma_f32_32x32x16_bf16 v[48:63], v[72:75], v[222:225], v[48:63]
	v_cvt_pk_bf16_f32 v88, v186, v187
	v_cvt_pk_bf16_f32 v89, v190, v191
	v_cvt_pk_bf16_f32 v90, v194, v195
	v_cvt_pk_bf16_f32 v91, v198, v199
	s_waitcnt lgkmcnt(0)
	s_nop 0
	v_mfma_f32_32x32x16_bf16 v[48:63], v[88:91], v[226:229], v[48:63]
	s_waitcnt lgkmcnt(2)
	v_mfma_f32_32x32x16_bf16 v[32:47], v[68:71], v[230:233], v[32:47]
	v_add_f32_e64 v68, v80, 0
	v_add_f32_e64 v69, v81, 0
	v_add_f32_e64 v64, v64, v68
	v_add_f32_e64 v65, v65, v69
	v_add_f32_e64 v64, v82, v64
	v_add_f32_e64 v65, v83, v65
	v_pk_add_f32 v[64:65], v[66:67], v[64:65]
	s_waitcnt lgkmcnt(0)
	v_mfma_f32_32x32x16_bf16 v[32:47], v[84:87], v[234:237], v[32:47]
	v_add_f32_e64 v64, v176, v64
	v_add_f32_e64 v65, v177, v65
	v_add_f32_e64 v64, v178, v64
	v_add_f32_e64 v65, v179, v65
	v_add_f32_e64 v64, v180, v64
	v_add_f32_e64 v65, v181, v65
	v_pk_add_f32 v[68:69], v[182:183], v[64:65]
	s_waitcnt lgkmcnt(0)
	v_mfma_f32_32x32x16_bf16 v[32:47], v[72:75], v[238:241], v[32:47]
	v_add_f32_e64 v68, v184, v68
	v_add_f32_e64 v69, v185, v69
	v_add_f32_e64 v76, v186, v68
	v_add_f32_e64 v77, v187, v69
	v_pk_add_f32 v[64:65], v[188:189], v[76:77]
	s_nop 0
	v_pk_add_f32 v[64:65], v[190:191], v[64:65]
	s_waitcnt lgkmcnt(0)
	v_mfma_f32_32x32x16_bf16 v[32:47], v[88:91], v[242:245], v[32:47]
	v_add_f32_e64 v64, v192, v64
	v_add_f32_e64 v65, v193, v65
	v_add_f32_e64 v64, v194, v64
	v_add_f32_e64 v65, v195, v65
	v_add_f32_e64 v64, v196, v64
	v_add_f32_e64 v65, v197, v65
	v_pk_add_f32 v[64:65], v[198:199], v[64:65]
	s_nop 0
	v_add_f32_e32 v64, v64, v65
	v_add_f32_e32 v175, v175, v64
	s_branch .LBB0_445

; template <int TYPE> __device__ __forceinline__ void attn_unit(const AttnCtx& C, int b, int h, int qb, LAS unsigned char* lds, int tid_in, unsigned* counter) {
;     ...
;             const bool active = (TYPE == 2) ? (t >= cq - 8 && t <= cq) : (TYPE == 0) ? (t <= cq && (float)(256 * qb + 32 * w - 64 * t - 63) < dmax) : (t <= cq && t >= tfirst);
;             if (active) {
;                 f32x16 p0, p1;
;                 const LAS unsigned char* kp = Kb + bo + hi * 1024 + r32 * 16;
; #pragma unroll
;                 for (int d0 = 0; d0 < 4; ++d0) {
;                     const bf16x8 a0 = *(const LAS bf16x8*)(kp + d0 * 2048), a1 = *(const LAS bf16x8*)(kp + d0 * 2048 + 512);
;                     if (d0 == 0) { p0 = MFMA32(a0, qr[0], (TYPE == 1 ? cvec : zvec)); p1 = MFMA32(a1, qr[0], (TYPE == 1 ? cvec : zvec)); }
;                     else { p0 = MFMA32(a0, qr[d0], p0); p1 = MFMA32(a1, qr[d0], p1); }
;                 }
;                 const int xi = sq - 64 * t - 4 * hi;
;                 if (TYPE == 0) {
;                     const float xf = (float)xi;
; #pragma unroll
;                     for (int r = 0; r < 16; ++r) { const float c = (float)((r & 3) + 8 * (r >> 2));
;                         p0[r] = fast_exp2(p0[r] - sl2 * fabsf(xf - c)); p1[r] = fast_exp2(p1[r] - sl2 * fabsf(xf - (c + 32.f))); }
;                 } else if (TYPE == 1) {
;                     const LAS float* fp = Fb + (t & 3) * 64 + 4 * hi;
; #pragma unroll
;                     for (int g = 0; g < 4; ++g) { const f32x4 fa = *(const LAS f32x4*)(fp + 8 * g), fb2 = *(const LAS f32x4*)(fp + 32 + 8 * g);
; #pragma unroll
;                         for (int i = 0; i < 4; i += 2) {
;                             const f32x2_t d0_ = (f32x2_t){p0[4 * g + i], p0[4 * g + i + 1]} - (f32x2_t){fa[i], fa[i + 1]}, d1_ = (f32x2_t){p1[4 * g + i], p1[4 * g + i + 1]} - (f32x2_t){fb2[i], fb2[i + 1]};
;                             p0[4 * g + i] = fast_exp2(d0_[0]); p0[4 * g + i + 1] = fast_exp2(d0_[1]); p1[4 * g + i] = fast_exp2(d1_[0]); p1[4 * g + i + 1] = fast_exp2(d1_[1]); } }
;                     if (t == cq) { const int qrel = 32 * (w & 1) + r32;
; #pragma unroll
;                         for (int r = 0; r < 16; ++r) { const int kv = crow(r, hi); if (kv > qrel) p0[r] = 0.f; if (kv + 32 > qrel) p1[r] = 0.f; } }
;                 } else {
;                     if (cq - t >= 3) { const float bc = relb[256];
.LBB0_1364:
	s_cmp_gt_i32 s3, s12
	s_cbranch_scc1 .LBB0_1359
	s_sub_i32 s7, s0, 63
	v_cvt_f32_i32_e32 v32, s7
	v_cmp_ngt_f32_e32 vcc, v168, v32
	s_cbranch_vccnz .LBB0_1359
	s_cmp_eq_u32 s3, s12
	s_cbranch_scc1 .Lt0diag_2
	v_add_u32_e32 v118, s6, v171
	v_add_u32_e32 v213, s0, v172
	v_cvt_f32_i32_e32 v213, v213
	v_mul_f32_e64 v210, -v167, v213
	ds_read_b128 v[202:205], v118
	ds_read_b128 v[206:209], v118 offset:512
	ds_read_b128 v[110:113], v118 offset:2048
	ds_read_b128 v[114:117], v118 offset:2560
	ds_read_b128 v[122:125], v118 offset:4608
	ds_read_b128 v[126:129], v118 offset:6144
	ds_read_b128 v[130:133], v118 offset:6656
	ds_read_b128 v[118:121], v118 offset:4096
	v_add_u32_e32 v134, s6, v170
	ds_read_b64_tr_b16 v[214:215], v134 offset:32768
	ds_read_b64_tr_b16 v[216:217], v134 offset:33280
	ds_read_b64_tr_b16 v[218:219], v134 offset:33792
	ds_read_b64_tr_b16 v[220:221], v134 offset:34304
	ds_read_b64_tr_b16 v[222:223], v134 offset:34816
	ds_read_b64_tr_b16 v[224:225], v134 offset:35328
	ds_read_b64_tr_b16 v[226:227], v134 offset:35840
	ds_read_b64_tr_b16 v[228:229], v134 offset:36352
	ds_read_b64_tr_b16 v[230:231], v134 offset:36864
	ds_read_b64_tr_b16 v[232:233], v134 offset:37376
	ds_read_b64_tr_b16 v[234:235], v134 offset:37888
	ds_read_b64_tr_b16 v[236:237], v134 offset:38400
	ds_read_b64_tr_b16 v[238:239], v134 offset:38912
	ds_read_b64_tr_b16 v[240:241], v134 offset:39424
	ds_read_b64_tr_b16 v[242:243], v134 offset:39936
	ds_read_b64_tr_b16 v[244:245], v134 offset:40448
	v_mov_b32_e32 v48, v210
	v_fmamk_f32 v49, v167, 0x3f800000, v210
	v_fmamk_f32 v50, v167, 0x40000000, v210
	v_fmamk_f32 v51, v167, 0x40400000, v210
	v_fmamk_f32 v52, v167, 0x41000000, v210
	v_fmamk_f32 v53, v167, 0x41100000, v210
	v_fmamk_f32 v54, v167, 0x41200000, v210
	v_fmamk_f32 v55, v167, 0x41300000, v210
	v_fmamk_f32 v56, v167, 0x41800000, v210
	v_fmamk_f32 v57, v167, 0x41880000, v210
	v_fmamk_f32 v58, v167, 0x41900000, v210
	v_fmamk_f32 v59, v167, 0x41980000, v210
	v_fmamk_f32 v60, v167, 0x41c00000, v210
	v_fmamk_f32 v61, v167, 0x41c80000, v210
	v_fmamk_f32 v62, v167, 0x41d00000, v210
	v_fmamk_f32 v63, v167, 0x41d80000, v210
	v_fmamk_f32 v32, v167, 0x42000000, v210
	v_fmamk_f32 v33, v167, 0x42040000, v210
	v_fmamk_f32 v34, v167, 0x42080000, v210
	v_fmamk_f32 v35, v167, 0x420c0000, v210
	v_fmamk_f32 v36, v167, 0x42200000, v210
	v_fmamk_f32 v37, v167, 0x42240000, v210
	v_fmamk_f32 v38, v167, 0x42280000, v210
	v_fmamk_f32 v39, v167, 0x422c0000, v210
	v_fmamk_f32 v40, v167, 0x42400000, v210
	v_fmamk_f32 v41, v167, 0x42440000, v210
	v_fmamk_f32 v42, v167, 0x42480000, v210
	v_fmamk_f32 v43, v167, 0x424c0000, v210
	v_fmamk_f32 v44, v167, 0x42600000, v210
	v_fmamk_f32 v45, v167, 0x42640000, v210
	v_fmamk_f32 v46, v167, 0x42680000, v210
	v_fmamk_f32 v47, v167, 0x426c0000, v210
	s_waitcnt vmcnt(7)
	s_waitcnt lgkmcnt(15)
	v_mfma_f32_32x32x16_bf16 v[48:63], v[202:205], v[64:67], v[48:63]
	v_mfma_f32_32x32x16_bf16 v[32:47], v[206:209], v[64:67], v[32:47]
	s_waitcnt vmcnt(6)
	v_mfma_f32_32x32x16_bf16 v[32:47], v[114:117], v[68:71], v[32:47]
	v_mfma_f32_32x32x16_bf16 v[48:63], v[110:113], v[68:71], v[48:63]
	s_waitcnt vmcnt(5)
	v_mfma_f32_32x32x16_bf16 v[32:47], v[122:125], v[72:75], v[32:47]
	v_mfma_f32_32x32x16_bf16 v[48:63], v[118:121], v[72:75], v[48:63]
	s_waitcnt vmcnt(4)
	v_mfma_f32_32x32x16_bf16 v[32:47], v[130:133], v[76:79], v[32:47]
	v_mfma_f32_32x32x16_bf16 v[48:63], v[126:129], v[76:79], v[48:63]
	s_nop 11
	v_exp_f32_e32 v32, v32
	v_exp_f32_e32 v110, v52
	v_exp_f32_e32 v112, v36
	v_exp_f32_e32 v111, v53
	v_exp_f32_e32 v113, v37
	v_exp_f32_e32 v114, v54
	v_exp_f32_e32 v116, v38
	v_exp_f32_e32 v115, v55
	v_exp_f32_e32 v117, v39
	v_exp_f32_e32 v118, v56
	v_exp_f32_e32 v120, v40
	v_exp_f32_e32 v119, v57
	v_exp_f32_e32 v121, v41
	v_exp_f32_e32 v122, v58
	v_exp_f32_e32 v124, v42
	v_exp_f32_e32 v123, v59
	v_exp_f32_e32 v125, v43
	v_exp_f32_e32 v126, v60
	v_exp_f32_e32 v128, v44
	v_exp_f32_e32 v127, v61
	v_exp_f32_e32 v129, v45
	v_exp_f32_e32 v48, v48
	v_exp_f32_e32 v49, v49
	v_exp_f32_e32 v50, v50
	v_exp_f32_e32 v51, v51
	v_exp_f32_e32 v130, v62
	v_exp_f32_e32 v132, v46
	v_exp_f32_e32 v131, v63
	v_cvt_pk_bf16_f32 v36, v48, v49
	v_cvt_pk_bf16_f32 v37, v50, v51
	v_cvt_pk_bf16_f32 v38, v110, v111
	v_cvt_pk_bf16_f32 v39, v114, v115
	s_waitcnt lgkmcnt(0)
	s_nop 0
	v_mfma_f32_32x32x16_bf16 v[16:31], v[36:39], v[214:217], v[16:31]
	v_cvt_pk_bf16_f32 v52, v118, v119
	v_cvt_pk_bf16_f32 v53, v122, v123
	v_cvt_pk_bf16_f32 v54, v126, v127
	v_cvt_pk_bf16_f32 v55, v130, v131
	v_exp_f32_e32 v33, v33
	v_exp_f32_e32 v34, v34
	v_exp_f32_e32 v35, v35
	s_waitcnt lgkmcnt(0)
	v_mfma_f32_32x32x16_bf16 v[16:31], v[52:55], v[218:221], v[16:31]
	v_exp_f32_e32 v133, v47
	v_cvt_pk_bf16_f32 v40, v32, v33
	v_cvt_pk_bf16_f32 v41, v34, v35
	v_cvt_pk_bf16_f32 v42, v112, v113
	v_cvt_pk_bf16_f32 v43, v116, v117
	s_waitcnt lgkmcnt(0)
	s_nop 0
	v_mfma_f32_32x32x16_bf16 v[16:31], v[40:43], v[222:225], v[16:31]
	v_cvt_pk_bf16_f32 v56, v120, v121
	v_cvt_pk_bf16_f32 v57, v124, v125
	v_cvt_pk_bf16_f32 v58, v128, v129
	v_cvt_pk_bf16_f32 v59, v132, v133
	s_waitcnt lgkmcnt(0)
	s_nop 0
	v_mfma_f32_32x32x16_bf16 v[16:31], v[56:59], v[226:229], v[16:31]
	s_waitcnt lgkmcnt(2)
	v_mfma_f32_32x32x16_bf16 v[0:15], v[36:39], v[230:233], v[0:15]
	v_add_f32_e64 v36, v48, 0
	v_add_f32_e64 v37, v49, 0
	v_add_f32_e64 v32, v32, v36
	v_add_f32_e64 v33, v33, v37
	v_add_f32_e64 v32, v50, v32
	v_add_f32_e64 v33, v51, v33
	v_pk_add_f32 v[32:33], v[34:35], v[32:33]
	s_waitcnt lgkmcnt(0)
	v_mfma_f32_32x32x16_bf16 v[0:15], v[52:55], v[234:237], v[0:15]
	v_add_f32_e64 v32, v110, v32
	v_add_f32_e64 v33, v111, v33
	v_add_f32_e64 v32, v112, v32
	v_add_f32_e64 v33, v113, v33
	v_add_f32_e64 v32, v114, v32
	v_add_f32_e64 v33, v115, v33
	v_pk_add_f32 v[36:37], v[116:117], v[32:33]
	s_waitcnt lgkmcnt(0)
	v_mfma_f32_32x32x16_bf16 v[0:15], v[40:43], v[238:241], v[0:15]
	v_add_f32_e64 v36, v118, v36
	v_add_f32_e64 v37, v119, v37
	v_add_f32_e64 v44, v120, v36
	v_add_f32_e64 v45, v121, v37
	v_pk_add_f32 v[32:33], v[122:123], v[44:45]
	s_nop 0
	v_pk_add_f32 v[32:33], v[124:125], v[32:33]
	s_waitcnt lgkmcnt(0)
	v_mfma_f32_32x32x16_bf16 v[0:15], v[56:59], v[242:245], v[0:15]
	v_add_f32_e64 v32, v126, v32
	v_add_f32_e64 v33, v127, v33
	v_add_f32_e64 v32, v128, v32
	v_add_f32_e64 v33, v129, v33
	v_add_f32_e64 v32, v130, v32
	v_add_f32_e64 v33, v131, v33
	v_pk_add_f32 v[32:33], v[132:133], v[32:33]
	s_nop 0
	v_add_f32_e32 v32, v32, v33
	v_add_f32_e32 v109, v109, v32
	s_branch .LBB0_1359

; template <int TYPE> __device__ __forceinline__ void attn_unit(const AttnCtx& C, int b, int h, int qb, LAS unsigned char* lds, int tid_in, unsigned* counter) {
;     ...
;             const bool active = (TYPE == 2) ? (t >= cq - 8 && t <= cq) : (TYPE == 0) ? (t <= cq && (float)(256 * qb + 32 * w - 64 * t - 63) < dmax) : (t <= cq && t >= tfirst);
;             if (active) {
;                 f32x16 p0, p1;
;                 const LAS unsigned char* kp = Kb + bo + hi * 1024 + r32 * 16;
; #pragma unroll
;                 for (int d0 = 0; d0 < 4; ++d0) {
;                     const bf16x8 a0 = *(const LAS bf16x8*)(kp + d0 * 2048), a1 = *(const LAS bf16x8*)(kp + d0 * 2048 + 512);
;                     if (d0 == 0) { p0 = MFMA32(a0, qr[0], (TYPE == 1 ? cvec : zvec)); p1 = MFMA32(a1, qr[0], (TYPE == 1 ? cvec : zvec)); }
;                     else { p0 = MFMA32(a0, qr[d0], p0); p1 = MFMA32(a1, qr[d0], p1); }
;                 }
;                 const int xi = sq - 64 * t - 4 * hi;
;                 if (TYPE == 0) {
;                     const float xf = (float)xi;
; #pragma unroll
;                     for (int r = 0; r < 16; ++r) { const float c = (float)((r & 3) + 8 * (r >> 2));
;                         p0[r] = fast_exp2(p0[r] - sl2 * fabsf(xf - c)); p1[r] = fast_exp2(p1[r] - sl2 * fabsf(xf - (c + 32.f))); }
;                 } else if (TYPE == 1) {
;                     const LAS float* fp = Fb + (t & 3) * 64 + 4 * hi;
; #pragma unroll
;                     for (int g = 0; g < 4; ++g) { const f32x4 fa = *(const LAS f32x4*)(fp + 8 * g), fb2 = *(const LAS f32x4*)(fp + 32 + 8 * g);
; #pragma unroll
;                         for (int i = 0; i < 4; i += 2) {
;                             const f32x2_t d0_ = (f32x2_t){p0[4 * g + i], p0[4 * g + i + 1]} - (f32x2_t){fa[i], fa[i + 1]}, d1_ = (f32x2_t){p1[4 * g + i], p1[4 * g + i + 1]} - (f32x2_t){fb2[i], fb2[i + 1]};
;                             p0[4 * g + i] = fast_exp2(d0_[0]); p0[4 * g + i + 1] = fast_exp2(d0_[1]); p1[4 * g + i] = fast_exp2(d1_[0]); p1[4 * g + i + 1] = fast_exp2(d1_[1]); } }
;                     if (t == cq) { const int qrel = 32 * (w & 1) + r32;
; #pragma unroll
;                         for (int r = 0; r < 16; ++r) { const int kv = crow(r, hi); if (kv > qrel) p0[r] = 0.f; if (kv + 32 > qrel) p1[r] = 0.f; } }
;                 } else {
;                     if (cq - t >= 3) { const float bc = relb[256];
.LBB0_1380:
	s_cmp_gt_i32 s13, s12
	s_cbranch_scc1 .LBB0_1371
	s_sub_i32 s0, s15, 63
	s_waitcnt vmcnt(15)
	v_cvt_f32_i32_e32 v64, s0
	v_cmp_ngt_f32_e32 vcc, v168, v64
	s_cbranch_vccnz .LBB0_1371
	s_cmp_eq_u32 s13, s12
	s_cbranch_scc1 .Lt0diag_1
	v_add_u32_e32 v184, s17, v171
	v_add_u32_e32 v213, s15, v172
	v_cvt_f32_i32_e32 v213, v213
	v_mul_f32_e64 v210, -v167, v213
	ds_read_b128 v[202:205], v184
	ds_read_b128 v[206:209], v184 offset:512
	ds_read_b128 v[176:179], v184 offset:2048
	ds_read_b128 v[180:183], v184 offset:2560
	ds_read_b128 v[188:191], v184 offset:4608
	ds_read_b128 v[192:195], v184 offset:6144
	ds_read_b128 v[196:199], v184 offset:6656
	ds_read_b128 v[184:187], v184 offset:4096
	s_waitcnt vmcnt(14)
	v_add_u32_e32 v200, s17, v170
	ds_read_b64_tr_b16 v[214:215], v200 offset:32768
	ds_read_b64_tr_b16 v[216:217], v200 offset:33280
	ds_read_b64_tr_b16 v[218:219], v200 offset:33792
	ds_read_b64_tr_b16 v[220:221], v200 offset:34304
	ds_read_b64_tr_b16 v[222:223], v200 offset:34816
	ds_read_b64_tr_b16 v[224:225], v200 offset:35328
	ds_read_b64_tr_b16 v[226:227], v200 offset:35840
	ds_read_b64_tr_b16 v[228:229], v200 offset:36352
	ds_read_b64_tr_b16 v[230:231], v200 offset:36864
	ds_read_b64_tr_b16 v[232:233], v200 offset:37376
	ds_read_b64_tr_b16 v[234:235], v200 offset:37888
	ds_read_b64_tr_b16 v[236:237], v200 offset:38400
	ds_read_b64_tr_b16 v[238:239], v200 offset:38912
	ds_read_b64_tr_b16 v[240:241], v200 offset:39424
	ds_read_b64_tr_b16 v[242:243], v200 offset:39936
	ds_read_b64_tr_b16 v[244:245], v200 offset:40448
	v_mov_b32_e32 v80, v210
	v_fmamk_f32 v81, v167, 0x3f800000, v210
	v_fmamk_f32 v82, v167, 0x40000000, v210
	v_fmamk_f32 v83, v167, 0x40400000, v210
	v_fmamk_f32 v84, v167, 0x41000000, v210
	v_fmamk_f32 v85, v167, 0x41100000, v210
	v_fmamk_f32 v86, v167, 0x41200000, v210
	v_fmamk_f32 v87, v167, 0x41300000, v210
	v_fmamk_f32 v88, v167, 0x41800000, v210
	v_fmamk_f32 v89, v167, 0x41880000, v210
	v_fmamk_f32 v90, v167, 0x41900000, v210
	v_fmamk_f32 v91, v167, 0x41980000, v210
	v_fmamk_f32 v92, v167, 0x41c00000, v210
	v_fmamk_f32 v93, v167, 0x41c80000, v210
	v_fmamk_f32 v94, v167, 0x41d00000, v210
	v_fmamk_f32 v95, v167, 0x41d80000, v210
	v_fmamk_f32 v64, v167, 0x42000000, v210
	v_fmamk_f32 v65, v167, 0x42040000, v210
	v_fmamk_f32 v66, v167, 0x42080000, v210
	v_fmamk_f32 v67, v167, 0x420c0000, v210
	v_fmamk_f32 v68, v167, 0x42200000, v210
	v_fmamk_f32 v69, v167, 0x42240000, v210
	v_fmamk_f32 v70, v167, 0x42280000, v210
	v_fmamk_f32 v71, v167, 0x422c0000, v210
	v_fmamk_f32 v72, v167, 0x42400000, v210
	v_fmamk_f32 v73, v167, 0x42440000, v210
	v_fmamk_f32 v74, v167, 0x42480000, v210
	v_fmamk_f32 v75, v167, 0x424c0000, v210
	v_fmamk_f32 v76, v167, 0x42600000, v210
	v_fmamk_f32 v77, v167, 0x42640000, v210
	v_fmamk_f32 v78, v167, 0x42680000, v210
	v_fmamk_f32 v79, v167, 0x426c0000, v210
	s_waitcnt vmcnt(7)
	s_waitcnt lgkmcnt(15)
	v_mfma_f32_32x32x16_bf16 v[80:95], v[202:205], v[112:115], v[80:95]
	v_mfma_f32_32x32x16_bf16 v[64:79], v[206:209], v[112:115], v[64:79]
	s_waitcnt vmcnt(6)
	v_mfma_f32_32x32x16_bf16 v[64:79], v[180:183], v[116:119], v[64:79]
	v_mfma_f32_32x32x16_bf16 v[80:95], v[176:179], v[116:119], v[80:95]
	s_waitcnt vmcnt(5)
	v_mfma_f32_32x32x16_bf16 v[64:79], v[188:191], v[120:123], v[64:79]
	v_mfma_f32_32x32x16_bf16 v[80:95], v[184:187], v[120:123], v[80:95]
	s_waitcnt vmcnt(4)
	v_mfma_f32_32x32x16_bf16 v[64:79], v[196:199], v[124:127], v[64:79]
	v_mfma_f32_32x32x16_bf16 v[80:95], v[192:195], v[124:127], v[80:95]
	s_nop 11
	v_exp_f32_e32 v64, v64
	v_exp_f32_e32 v176, v84
	v_exp_f32_e32 v178, v68
	v_exp_f32_e32 v177, v85
	v_exp_f32_e32 v179, v69
	v_exp_f32_e32 v180, v86
	v_exp_f32_e32 v182, v70
	v_exp_f32_e32 v181, v87
	v_exp_f32_e32 v183, v71
	v_exp_f32_e32 v184, v88
	v_exp_f32_e32 v186, v72
	v_exp_f32_e32 v185, v89
	v_exp_f32_e32 v187, v73
	v_exp_f32_e32 v188, v90
	v_exp_f32_e32 v190, v74
	v_exp_f32_e32 v189, v91
	v_exp_f32_e32 v191, v75
	v_exp_f32_e32 v192, v92
	v_exp_f32_e32 v194, v76
	v_exp_f32_e32 v193, v93
	v_exp_f32_e32 v195, v77
	v_exp_f32_e32 v80, v80
	v_exp_f32_e32 v81, v81
	v_exp_f32_e32 v82, v82
	v_exp_f32_e32 v83, v83
	v_exp_f32_e32 v196, v94
	v_exp_f32_e32 v198, v78
	v_exp_f32_e32 v197, v95
	v_cvt_pk_bf16_f32 v68, v80, v81
	v_cvt_pk_bf16_f32 v69, v82, v83
	v_cvt_pk_bf16_f32 v70, v176, v177
	v_cvt_pk_bf16_f32 v71, v180, v181
	s_waitcnt lgkmcnt(0)
	s_nop 0
	v_mfma_f32_32x32x16_bf16 v[48:63], v[68:71], v[214:217], v[48:63]
	v_cvt_pk_bf16_f32 v84, v184, v185
	v_cvt_pk_bf16_f32 v85, v188, v189
	v_cvt_pk_bf16_f32 v86, v192, v193
	v_cvt_pk_bf16_f32 v87, v196, v197
	v_exp_f32_e32 v65, v65
	v_exp_f32_e32 v66, v66
	v_exp_f32_e32 v67, v67
	s_waitcnt lgkmcnt(0)
	v_mfma_f32_32x32x16_bf16 v[48:63], v[84:87], v[218:221], v[48:63]
	v_exp_f32_e32 v199, v79
	v_cvt_pk_bf16_f32 v72, v64, v65
	v_cvt_pk_bf16_f32 v73, v66, v67
	v_cvt_pk_bf16_f32 v74, v178, v179
	v_cvt_pk_bf16_f32 v75, v182, v183
	s_waitcnt lgkmcnt(0)
	s_nop 0
	v_mfma_f32_32x32x16_bf16 v[48:63], v[72:75], v[222:225], v[48:63]
	v_cvt_pk_bf16_f32 v88, v186, v187
	v_cvt_pk_bf16_f32 v89, v190, v191
	v_cvt_pk_bf16_f32 v90, v194, v195
	v_cvt_pk_bf16_f32 v91, v198, v199
	s_waitcnt lgkmcnt(0)
	s_nop 0
	v_mfma_f32_32x32x16_bf16 v[48:63], v[88:91], v[226:229], v[48:63]
	s_waitcnt lgkmcnt(2)
	v_mfma_f32_32x32x16_bf16 v[32:47], v[68:71], v[230:233], v[32:47]
	v_add_f32_e64 v68, v80, 0
	v_add_f32_e64 v69, v81, 0
	v_add_f32_e64 v64, v64, v68
	v_add_f32_e64 v65, v65, v69
	v_add_f32_e64 v64, v82, v64
	v_add_f32_e64 v65, v83, v65
	v_pk_add_f32 v[64:65], v[66:67], v[64:65]
	s_waitcnt lgkmcnt(0)
	v_mfma_f32_32x32x16_bf16 v[32:47], v[84:87], v[234:237], v[32:47]
	v_add_f32_e64 v64, v176, v64
	v_add_f32_e64 v65, v177, v65
	v_add_f32_e64 v64, v178, v64
	v_add_f32_e64 v65, v179, v65
	v_add_f32_e64 v64, v180, v64
	v_add_f32_e64 v65, v181, v65
	v_pk_add_f32 v[68:69], v[182:183], v[64:65]
	s_waitcnt lgkmcnt(0)
	v_mfma_f32_32x32x16_bf16 v[32:47], v[72:75], v[238:241], v[32:47]
	v_add_f32_e64 v68, v184, v68
	v_add_f32_e64 v69, v185, v69
	v_add_f32_e64 v76, v186, v68
	v_add_f32_e64 v77, v187, v69
	v_pk_add_f32 v[64:65], v[188:189], v[76:77]
	s_nop 0
	v_pk_add_f32 v[64:65], v[190:191], v[64:65]
	s_waitcnt lgkmcnt(0)
	v_mfma_f32_32x32x16_bf16 v[32:47], v[88:91], v[242:245], v[32:47]
	v_add_f32_e64 v64, v192, v64
	v_add_f32_e64 v65, v193, v65
	v_add_f32_e64 v64, v194, v64
	v_add_f32_e64 v65, v195, v65
	v_add_f32_e64 v64, v196, v64
	v_add_f32_e64 v65, v197, v65
	v_pk_add_f32 v[64:65], v[198:199], v[64:65]
	s_nop 0
	v_add_f32_e32 v64, v64, v65
	v_add_f32_e32 v175, v175, v64
	s_branch .LBB0_1371
